# silu scale constant held in an SGPR (4-byte encodings in the up epilogue) plus static s_setprio 1 for waves 4-7 in attention
# speedup vs baseline: 1.0055x; 1.0005x over previous
; #define PG8_STAGE(bufoff, gbase, voff) do { _Pragma("unroll") for (int _i = 0; _i < 2; ++_i) \
;         __builtin_amdgcn_global_load_lds((const unsigned*)((const char*)(gbase) + (size_t)_i * r64##voff + voff), (PG8_LAS unsigned*)(lds + (bufoff) + ldsw + _i * 8192), 16, 0, 0); } while (0)
; #define PG8_LDA(dst, b, h) do { _Pragma("unroll") for (int m = 0; m < 4; ++m) _Pragma("unroll") for (int k = 0; k < 2; ++k) dst[m][k] = *(const PG8_LAS bf16x8*)(lds + PG8_SA(b, h) + aoff + m * 2048 + k * 1024); } while (0)
; #define PG8_LDB(dst, b, h) do { _Pragma("unroll") for (int n = 0; n < 2; ++n) _Pragma("unroll") for (int k = 0; k < 2; ++k) dst[n][k] = *(const PG8_LAS bf16x8*)(lds + PG8_SB(b, h) + boff + n * 2048 + k * 1024); } while (0)
; #define PG8_MMA(ai, bj, At, Bt) do { __builtin_amdgcn_s_setprio(1); _Pragma("unroll") for (int m = 0; m < 4; ++m) _Pragma("unroll") for (int n = 0; n < 2; ++n) _Pragma("unroll") for (int k = 0; k < 2; ++k) \
;         acc[ai][bj][m][n] = __builtin_amdgcn_mfma_f32_16x16x32_bf16(Bt[n][k], At[m][k], acc[ai][bj][m][n], 0, 0, 0); __builtin_amdgcn_s_setprio(0); } while (0)
; #define PG8_WAIT_V(n) asm volatile("s_waitcnt vmcnt(" #n ")" ::: "memory")
; #define PG8_WAIT_L(n) asm volatile("s_waitcnt lgkmcnt(" #n ")" ::: "memory")
; template <class Epi, class Sched, bool ALIGN_EPI = false, bool SP2 = false>
; __device__ __forceinline__ void gemm_phase(PG8_LAS unsigned char* lds, const Gemm g, const Sched& S, const Epi& E, int wid0) {
;     ...
;             const bool last = (t == nt - 2);
;             const char* a1 = cA + (size_t)(t + 1) * kstep;
;             const char* a2 = last ? nA : cA + (size_t)(t + 2) * kstep; const char* b2 = last ? nB : cB + (size_t)(t + 2) * kstep;
;             const char* a3 = a2 + kstep; const char* b3 = b2 + kstep;
;             if (last && has_next) S.a_ready(nxt);
;             if constexpr (SP2) {
;             PG8_LDB(B0, 0, 0); PG8_LDB(B1, 0, 1); PG8_SCHED; PG8_LDA(At, 0, 0); PG8_STAGE(PG8_SA(1, 1), a1 + hstepA, voffA);
;             PG8_WAIT_V(8); PG8_WAIT_L(0); PG8_BAR; PG8_MMA(0, 0, At, B0); PG8_MMA(0, 1, At, B1); PG8_BAR; PG8_SCHED;
;             PG8_LDA(At, 0, 1); PG8_STAGE(PG8_SB(0, 0), b2, voffB); PG8_STAGE(PG8_SB(0, 1), b2 + hstepB, voffB); PG8_STAGE(PG8_SA(0, 0), a2, voffA);
;             PG8_WAIT_V(8); PG8_WAIT_L(0); PG8_BAR; PG8_MMA(1, 0, At, B0); PG8_MMA(1, 1, At, B1); PG8_BAR; PG8_SCHED;
.LBB0_556:
	s_add_u32 s14, s4, 0xfffc0080
	s_addc_u32 s15, s5, -1
	s_add_i32 s63, 0, 0x10000
	s_cmp_eq_u32 vcc_hi, 12
	s_cselect_b32 s15, s79, s15
	s_cselect_b32 s14, s78, s14
	s_cselect_b32 s95, s45, s47
	s_cselect_b32 s94, vcc_lo, s46
	s_add_i32 s22, 0, 0x14000
	v_add_u32_e32 v142, s63, v1
	v_add_u32_e32 v158, s22, v1
	ds_read_b128 v[102:105], v142
	ds_read_b128 v[134:137], v142 offset:1024
	ds_read_b128 v[138:141], v142 offset:2048
	ds_read_b128 v[142:145], v142 offset:3072
	ds_read_b128 v[146:149], v158
	ds_read_b128 v[150:153], v158 offset:1024
	ds_read_b128 v[154:157], v158 offset:2048
	ds_read_b128 v[158:161], v158 offset:3072
	v_lshl_add_u64 v[194:195], s[4:5], 0, v[206:207]
	s_add_i32 m0, s17, 0xc000
	ds_read_b128 v[162:165], v248
	ds_read_b128 v[166:169], v248 offset:1024
	ds_read_b128 v[170:173], v248 offset:2048
	ds_read_b128 v[174:177], v248 offset:3072
	ds_read_b128 v[178:181], v248 offset:4096
	ds_read_b128 v[182:185], v248 offset:5120
	ds_read_b128 v[186:189], v248 offset:6144
	ds_read_b128 v[190:193], v248 offset:7168
	global_load_lds_dwordx4 v[194:195], off
	v_lshl_add_u64 v[194:195], v[194:195], 0, s[64:65]
	s_add_i32 m0, s17, 0xe000
	s_nop 0
	global_load_lds_dwordx4 v[194:195], off
	s_waitcnt vmcnt(8)
	s_waitcnt lgkmcnt(0)
	s_barrier
	s_setprio 1
	s_waitcnt lgkmcnt(0)
	v_mfma_f32_16x16x32_bf16 v[130:133], v[102:105], v[162:165], v[130:133]
	v_mfma_f32_16x16x32_bf16 v[126:129], v[138:141], v[162:165], v[126:129]
	v_mfma_f32_16x16x32_bf16 v[122:125], v[102:105], v[170:173], v[122:125]
	v_mfma_f32_16x16x32_bf16 v[118:121], v[138:141], v[170:173], v[118:121]
	v_mfma_f32_16x16x32_bf16 v[78:81], v[102:105], v[178:181], v[78:81]
	v_mfma_f32_16x16x32_bf16 v[86:89], v[138:141], v[178:181], v[86:89]
	v_mfma_f32_16x16x32_bf16 v[106:109], v[102:105], v[186:189], v[106:109]
	v_mfma_f32_16x16x32_bf16 v[90:93], v[138:141], v[186:189], v[90:93]
	v_mfma_f32_16x16x32_bf16 v[130:133], v[134:137], v[166:169], v[130:133]
	v_mfma_f32_16x16x32_bf16 v[126:129], v[142:145], v[166:169], v[126:129]
	v_mfma_f32_16x16x32_bf16 v[122:125], v[134:137], v[174:177], v[122:125]
	v_mfma_f32_16x16x32_bf16 v[118:121], v[142:145], v[174:177], v[118:121]
	v_mfma_f32_16x16x32_bf16 v[78:81], v[134:137], v[182:185], v[78:81]
	v_mfma_f32_16x16x32_bf16 v[86:89], v[142:145], v[182:185], v[86:89]
	v_mfma_f32_16x16x32_bf16 v[106:109], v[134:137], v[190:193], v[106:109]
	v_mfma_f32_16x16x32_bf16 v[90:93], v[142:145], v[190:193], v[90:93]
	s_setprio 0
	s_setprio 1
	v_mfma_f32_16x16x32_bf16 v[114:117], v[146:149], v[162:165], v[114:117]
	v_mfma_f32_16x16x32_bf16 v[110:113], v[154:157], v[162:165], v[110:113]
	v_mfma_f32_16x16x32_bf16 v[98:101], v[146:149], v[170:173], v[98:101]
	v_mfma_f32_16x16x32_bf16 v[94:97], v[154:157], v[170:173], v[94:97]
	v_mfma_f32_16x16x32_bf16 v[82:85], v[146:149], v[178:181], v[82:85]
	v_mfma_f32_16x16x32_bf16 v[70:73], v[154:157], v[178:181], v[70:73]
	v_mfma_f32_16x16x32_bf16 v[74:77], v[146:149], v[186:189], v[74:77]
	v_mfma_f32_16x16x32_bf16 v[66:69], v[154:157], v[186:189], v[66:69]
	v_mfma_f32_16x16x32_bf16 v[114:117], v[150:153], v[166:169], v[114:117]
	v_mfma_f32_16x16x32_bf16 v[110:113], v[158:161], v[166:169], v[110:113]
	v_mfma_f32_16x16x32_bf16 v[98:101], v[150:153], v[174:177], v[98:101]
	v_mfma_f32_16x16x32_bf16 v[94:97], v[158:161], v[174:177], v[94:97]
	v_mfma_f32_16x16x32_bf16 v[82:85], v[150:153], v[182:185], v[82:85]
	v_mfma_f32_16x16x32_bf16 v[70:73], v[158:161], v[182:185], v[70:73]
	v_mfma_f32_16x16x32_bf16 v[74:77], v[150:153], v[190:193], v[74:77]
	v_mfma_f32_16x16x32_bf16 v[66:69], v[158:161], v[190:193], v[66:69]
	s_setprio 0
	s_barrier
	s_add_i32 s63, s63, s40
	v_lshl_add_u64 v[194:195], s[94:95], 0, v[204:205]
	s_mov_b32 m0, s63
	ds_read_b128 v[162:165], v248 offset:16384
	ds_read_b128 v[166:169], v248 offset:17408
	ds_read_b128 v[170:173], v248 offset:18432
	ds_read_b128 v[174:177], v248 offset:19456
	ds_read_b128 v[178:181], v248 offset:20480
	ds_read_b128 v[182:185], v248 offset:21504
	ds_read_b128 v[186:189], v248 offset:22528
	ds_read_b128 v[190:193], v248 offset:23552
	global_load_lds_dwordx4 v[194:195], off
	v_lshl_add_u64 v[196:197], v[194:195], 0, s[64:65]
	s_add_i32 m0, s63, 0x2000
	s_add_i32 s22, s22, s40
	global_load_lds_dwordx4 v[196:197], off
	v_lshl_add_u64 v[196:197], v[194:195], 0, s[66:67]
	s_mov_b32 m0, s22
	s_nop 0
	global_load_lds_dwordx4 v[196:197], off
	v_lshl_add_u64 v[196:197], v[194:195], 0, s[68:69]
	s_add_i32 m0, s22, 0x2000
	s_nop 0
	global_load_lds_dwordx4 v[196:197], off
	v_lshl_add_u64 v[196:197], s[14:15], 0, v[202:203]
	s_mov_b32 m0, s17
	v_lshl_add_u64 v[198:199], v[196:197], 0, s[64:65]
	global_load_lds_dwordx4 v[196:197], off
	s_mov_b32 m0, s93
	s_nop 0
	global_load_lds_dwordx4 v[198:199], off
	s_waitcnt vmcnt(8)
	s_waitcnt lgkmcnt(0)
	s_barrier
; #define PG8_STAGE(bufoff, gbase, voff) do { _Pragma("unroll") for (int _i = 0; _i < 2; ++_i) \
;         __builtin_amdgcn_global_load_lds((const unsigned*)((const char*)(gbase) + (size_t)_i * r64##voff + voff), (PG8_LAS unsigned*)(lds + (bufoff) + ldsw + _i * 8192), 16, 0, 0); } while (0)
; #define PG8_LDA(dst, b, h) do { _Pragma("unroll") for (int m = 0; m < 4; ++m) _Pragma("unroll") for (int k = 0; k < 2; ++k) dst[m][k] = *(const PG8_LAS bf16x8*)(lds + PG8_SA(b, h) + aoff + m * 2048 + k * 1024); } while (0)
; #define PG8_LDB(dst, b, h) do { _Pragma("unroll") for (int n = 0; n < 2; ++n) _Pragma("unroll") for (int k = 0; k < 2; ++k) dst[n][k] = *(const PG8_LAS bf16x8*)(lds + PG8_SB(b, h) + boff + n * 2048 + k * 1024); } while (0)
; #define PG8_MMA(ai, bj, At, Bt) do { __builtin_amdgcn_s_setprio(1); _Pragma("unroll") for (int m = 0; m < 4; ++m) _Pragma("unroll") for (int n = 0; n < 2; ++n) _Pragma("unroll") for (int k = 0; k < 2; ++k) \
;         acc[ai][bj][m][n] = __builtin_amdgcn_mfma_f32_16x16x32_bf16(Bt[n][k], At[m][k], acc[ai][bj][m][n], 0, 0, 0); __builtin_amdgcn_s_setprio(0); } while (0)
; #define PG8_WAIT_V(n) asm volatile("s_waitcnt vmcnt(" #n ")" ::: "memory")
; #define PG8_WAIT_L(n) asm volatile("s_waitcnt lgkmcnt(" #n ")" ::: "memory")
; #define PG8_BAR __builtin_amdgcn_s_barrier()
; #define PG8_SCHED __builtin_amdgcn_sched_barrier(0)
; template <class Epi, class Sched, bool ALIGN_EPI = false, bool SP2 = false>
; __device__ __forceinline__ void gemm_phase(PG8_LAS unsigned char* lds, const Gemm g, const Sched& S, const Epi& E, int wid0) {
;     ...
;             PG8_WAIT_V(8); PG8_WAIT_L(0); PG8_BAR; PG8_MMA(1, 0, At, B0); PG8_MMA(1, 1, At, B1); PG8_BAR; PG8_SCHED;
;             PG8_LDB(B0, 1, 0); PG8_LDB(B1, 1, 1); PG8_SCHED; PG8_LDA(At, 1, 0); PG8_STAGE(PG8_SA(0, 1), a2 + hstepA, voffA);
;             PG8_WAIT_V(8); PG8_WAIT_L(0); PG8_BAR; PG8_MMA(0, 0, At, B0); PG8_MMA(0, 1, At, B1); PG8_BAR; PG8_SCHED;
	s_setprio 1
	s_waitcnt lgkmcnt(0)
	v_mfma_f32_16x16x32_bf16 v[34:37], v[102:105], v[162:165], v[34:37]
	v_mfma_f32_16x16x32_bf16 v[30:33], v[138:141], v[162:165], v[30:33]
	v_mfma_f32_16x16x32_bf16 v[22:25], v[102:105], v[170:173], v[22:25]
	v_mfma_f32_16x16x32_bf16 v[18:21], v[138:141], v[170:173], v[18:21]
	v_mfma_f32_16x16x32_bf16 v[58:61], v[102:105], v[178:181], v[58:61]
	v_mfma_f32_16x16x32_bf16 v[50:53], v[138:141], v[178:181], v[50:53]
	v_mfma_f32_16x16x32_bf16 v[62:65], v[102:105], v[186:189], v[62:65]
	v_mfma_f32_16x16x32_bf16 v[54:57], v[138:141], v[186:189], v[54:57]
	v_mfma_f32_16x16x32_bf16 v[34:37], v[134:137], v[166:169], v[34:37]
	v_mfma_f32_16x16x32_bf16 v[30:33], v[142:145], v[166:169], v[30:33]
	v_mfma_f32_16x16x32_bf16 v[22:25], v[134:137], v[174:177], v[22:25]
	v_mfma_f32_16x16x32_bf16 v[18:21], v[142:145], v[174:177], v[18:21]
	v_mfma_f32_16x16x32_bf16 v[58:61], v[134:137], v[182:185], v[58:61]
	v_mfma_f32_16x16x32_bf16 v[50:53], v[142:145], v[182:185], v[50:53]
	v_mfma_f32_16x16x32_bf16 v[62:65], v[134:137], v[190:193], v[62:65]
	v_mfma_f32_16x16x32_bf16 v[54:57], v[142:145], v[190:193], v[54:57]
	s_setprio 0
	s_setprio 1
	v_mfma_f32_16x16x32_bf16 v[14:17], v[146:149], v[162:165], v[14:17]
	v_mfma_f32_16x16x32_bf16 v[10:13], v[154:157], v[162:165], v[10:13]
	v_mfma_f32_16x16x32_bf16 v[6:9], v[146:149], v[170:173], v[6:9]
	v_mfma_f32_16x16x32_bf16 v[2:5], v[154:157], v[170:173], v[2:5]
	v_mfma_f32_16x16x32_bf16 v[42:45], v[146:149], v[178:181], v[42:45]
	v_mfma_f32_16x16x32_bf16 v[26:29], v[154:157], v[178:181], v[26:29]
	v_mfma_f32_16x16x32_bf16 v[46:49], v[146:149], v[186:189], v[46:49]
	v_mfma_f32_16x16x32_bf16 v[38:41], v[154:157], v[186:189], v[38:41]
	v_mfma_f32_16x16x32_bf16 v[14:17], v[150:153], v[166:169], v[14:17]
	v_mfma_f32_16x16x32_bf16 v[10:13], v[158:161], v[166:169], v[10:13]
	v_mfma_f32_16x16x32_bf16 v[6:9], v[150:153], v[174:177], v[6:9]
	v_mfma_f32_16x16x32_bf16 v[2:5], v[158:161], v[174:177], v[2:5]
	v_mfma_f32_16x16x32_bf16 v[42:45], v[150:153], v[182:185], v[42:45]
	v_mfma_f32_16x16x32_bf16 v[26:29], v[158:161], v[182:185], v[26:29]
	v_mfma_f32_16x16x32_bf16 v[46:49], v[150:153], v[190:193], v[46:49]
	v_mfma_f32_16x16x32_bf16 v[38:41], v[158:161], v[190:193], v[38:41]
	s_setprio 0
	s_barrier
	s_add_i32 s14, 0, 0x18000
	s_add_i32 s15, 0, 0x1c000
	v_add_u32_e32 v142, s14, v1
	v_add_u32_e32 v158, s15, v1
	ds_read_b128 v[102:105], v142
	ds_read_b128 v[134:137], v142 offset:1024
	ds_read_b128 v[138:141], v142 offset:2048
	ds_read_b128 v[142:145], v142 offset:3072
	ds_read_b128 v[146:149], v158
	ds_read_b128 v[150:153], v158 offset:1024
	ds_read_b128 v[154:157], v158 offset:2048
	ds_read_b128 v[158:161], v158 offset:3072
	s_mov_b32 m0, s20
	v_lshl_add_u64 v[198:199], v[196:197], 0, s[66:67]
	ds_read_b128 v[162:165], v248 offset:32768
	ds_read_b128 v[166:169], v248 offset:33792
	ds_read_b128 v[170:173], v248 offset:34816
	ds_read_b128 v[174:177], v248 offset:35840
	ds_read_b128 v[178:181], v248 offset:36864
	ds_read_b128 v[182:185], v248 offset:37888
	ds_read_b128 v[186:189], v248 offset:38912
	ds_read_b128 v[190:193], v248 offset:39936
	global_load_lds_dwordx4 v[198:199], off
	v_lshl_add_u64 v[198:199], v[196:197], 0, s[68:69]
	s_mov_b32 m0, s21
	s_nop 0
	global_load_lds_dwordx4 v[198:199], off
	s_waitcnt vmcnt(8)
	s_waitcnt lgkmcnt(0)
	s_barrier
	s_setprio 1
	s_waitcnt lgkmcnt(0)
	v_mfma_f32_16x16x32_bf16 v[130:133], v[102:105], v[162:165], v[130:133]
	v_mfma_f32_16x16x32_bf16 v[126:129], v[138:141], v[162:165], v[126:129]
	v_mfma_f32_16x16x32_bf16 v[122:125], v[102:105], v[170:173], v[122:125]
	v_mfma_f32_16x16x32_bf16 v[118:121], v[138:141], v[170:173], v[118:121]
	v_mfma_f32_16x16x32_bf16 v[78:81], v[102:105], v[178:181], v[78:81]
	v_mfma_f32_16x16x32_bf16 v[86:89], v[138:141], v[178:181], v[86:89]
	v_mfma_f32_16x16x32_bf16 v[106:109], v[102:105], v[186:189], v[106:109]
	v_mfma_f32_16x16x32_bf16 v[90:93], v[138:141], v[186:189], v[90:93]
	v_mfma_f32_16x16x32_bf16 v[130:133], v[134:137], v[166:169], v[130:133]
	v_mfma_f32_16x16x32_bf16 v[126:129], v[142:145], v[166:169], v[126:129]
	v_mfma_f32_16x16x32_bf16 v[122:125], v[134:137], v[174:177], v[122:125]
	v_mfma_f32_16x16x32_bf16 v[118:121], v[142:145], v[174:177], v[118:121]
	v_mfma_f32_16x16x32_bf16 v[78:81], v[134:137], v[182:185], v[78:81]
	v_mfma_f32_16x16x32_bf16 v[86:89], v[142:145], v[182:185], v[86:89]
	v_mfma_f32_16x16x32_bf16 v[106:109], v[134:137], v[190:193], v[106:109]
	v_mfma_f32_16x16x32_bf16 v[90:93], v[142:145], v[190:193], v[90:93]
	s_setprio 0
	s_setprio 1
	v_mfma_f32_16x16x32_bf16 v[114:117], v[146:149], v[162:165], v[114:117]
	v_mfma_f32_16x16x32_bf16 v[110:113], v[154:157], v[162:165], v[110:113]
	v_mfma_f32_16x16x32_bf16 v[98:101], v[146:149], v[170:173], v[98:101]
	v_mfma_f32_16x16x32_bf16 v[94:97], v[154:157], v[170:173], v[94:97]
	v_mfma_f32_16x16x32_bf16 v[82:85], v[146:149], v[178:181], v[82:85]
	v_mfma_f32_16x16x32_bf16 v[70:73], v[154:157], v[178:181], v[70:73]
	v_mfma_f32_16x16x32_bf16 v[74:77], v[146:149], v[186:189], v[74:77]
	v_mfma_f32_16x16x32_bf16 v[66:69], v[154:157], v[186:189], v[66:69]
	v_mfma_f32_16x16x32_bf16 v[114:117], v[150:153], v[166:169], v[114:117]
	v_mfma_f32_16x16x32_bf16 v[110:113], v[158:161], v[166:169], v[110:113]
	v_mfma_f32_16x16x32_bf16 v[98:101], v[150:153], v[174:177], v[98:101]
	v_mfma_f32_16x16x32_bf16 v[94:97], v[158:161], v[174:177], v[94:97]
	v_mfma_f32_16x16x32_bf16 v[82:85], v[150:153], v[182:185], v[82:85]
	v_mfma_f32_16x16x32_bf16 v[70:73], v[158:161], v[182:185], v[70:73]
	v_mfma_f32_16x16x32_bf16 v[74:77], v[150:153], v[190:193], v[74:77]
	v_mfma_f32_16x16x32_bf16 v[66:69], v[158:161], v[190:193], v[66:69]
	s_setprio 0
	s_barrier
; #define PG8_STAGE(bufoff, gbase, voff) do { _Pragma("unroll") for (int _i = 0; _i < 2; ++_i) \
;         __builtin_amdgcn_global_load_lds((const unsigned*)((const char*)(gbase) + (size_t)_i * r64##voff + voff), (PG8_LAS unsigned*)(lds + (bufoff) + ldsw + _i * 8192), 16, 0, 0); } while (0)
; #define PG8_LDA(dst, b, h) do { _Pragma("unroll") for (int m = 0; m < 4; ++m) _Pragma("unroll") for (int k = 0; k < 2; ++k) dst[m][k] = *(const PG8_LAS bf16x8*)(lds + PG8_SA(b, h) + aoff + m * 2048 + k * 1024); } while (0)
; #define PG8_MMA(ai, bj, At, Bt) do { __builtin_amdgcn_s_setprio(1); _Pragma("unroll") for (int m = 0; m < 4; ++m) _Pragma("unroll") for (int n = 0; n < 2; ++n) _Pragma("unroll") for (int k = 0; k < 2; ++k) \
;         acc[ai][bj][m][n] = __builtin_amdgcn_mfma_f32_16x16x32_bf16(Bt[n][k], At[m][k], acc[ai][bj][m][n], 0, 0, 0); __builtin_amdgcn_s_setprio(0); } while (0)
; #define PG8_WAIT_V(n) asm volatile("s_waitcnt vmcnt(" #n ")" ::: "memory")
; #define PG8_WAIT_L(n) asm volatile("s_waitcnt lgkmcnt(" #n ")" ::: "memory")
; #define PG8_BAR __builtin_amdgcn_s_barrier()
; #define PG8_SCHED __builtin_amdgcn_sched_barrier(0)
; template <class Epi, class Sched, bool ALIGN_EPI = false, bool SP2 = false>
; __device__ __forceinline__ void gemm_phase(PG8_LAS unsigned char* lds, const Gemm g, const Sched& S, const Epi& E, int wid0) {
;     ...
;             PG8_LDA(At, 1, 1); PG8_STAGE(PG8_SB(1, 0), b3, voffB); PG8_STAGE(PG8_SB(1, 1), b3 + hstepB, voffB); PG8_STAGE(PG8_SA(1, 0), a3, voffA);
;             PG8_WAIT_V(8); PG8_WAIT_L(0); PG8_BAR; PG8_MMA(1, 0, At, B0); PG8_MMA(1, 1, At, B1); PG8_BAR; PG8_SCHED;
	s_add_i32 s14, s14, s40
	v_lshl_add_u64 v[198:199], v[194:195], 0, s[70:71]
	s_mov_b32 m0, s14
	ds_read_b128 v[162:165], v248 offset:49152
	ds_read_b128 v[166:169], v248 offset:50176
	ds_read_b128 v[170:173], v248 offset:51200
	ds_read_b128 v[174:177], v248 offset:52224
	ds_read_b128 v[178:181], v248 offset:53248
	ds_read_b128 v[182:185], v248 offset:54272
	ds_read_b128 v[186:189], v248 offset:55296
	ds_read_b128 v[190:193], v248 offset:56320
	global_load_lds_dwordx4 v[198:199], off
	v_lshl_add_u64 v[198:199], v[194:195], 0, s[72:73]
	s_add_i32 m0, s14, 0x2000
	s_add_i32 s14, s15, s40
	global_load_lds_dwordx4 v[198:199], off
	v_lshl_add_u64 v[198:199], v[194:195], 0, s[74:75]
	s_mov_b32 m0, s14
	v_lshl_add_u64 v[194:195], v[194:195], 0, s[76:77]
	global_load_lds_dwordx4 v[198:199], off
	s_add_i32 m0, s14, 0x2000
	s_nop 0
	global_load_lds_dwordx4 v[194:195], off
	v_lshl_add_u64 v[194:195], v[196:197], 0, s[70:71]
	s_mov_b32 m0, s18
	s_nop 0
	global_load_lds_dwordx4 v[194:195], off
	v_lshl_add_u64 v[194:195], v[196:197], 0, s[72:73]
	s_mov_b32 m0, s19
	s_nop 0
	global_load_lds_dwordx4 v[194:195], off
	s_waitcnt vmcnt(8)
	s_waitcnt lgkmcnt(0)
	s_barrier
	s_setprio 1
	s_waitcnt lgkmcnt(0)
	v_mfma_f32_16x16x32_bf16 v[34:37], v[102:105], v[162:165], v[34:37]
	v_mfma_f32_16x16x32_bf16 v[30:33], v[138:141], v[162:165], v[30:33]
	v_mfma_f32_16x16x32_bf16 v[22:25], v[102:105], v[170:173], v[22:25]
	v_mfma_f32_16x16x32_bf16 v[18:21], v[138:141], v[170:173], v[18:21]
	v_mfma_f32_16x16x32_bf16 v[58:61], v[102:105], v[178:181], v[58:61]
	v_mfma_f32_16x16x32_bf16 v[50:53], v[138:141], v[178:181], v[50:53]
	v_mfma_f32_16x16x32_bf16 v[62:65], v[102:105], v[186:189], v[62:65]
	v_mfma_f32_16x16x32_bf16 v[54:57], v[138:141], v[186:189], v[54:57]
	v_mfma_f32_16x16x32_bf16 v[34:37], v[134:137], v[166:169], v[34:37]
	v_mfma_f32_16x16x32_bf16 v[30:33], v[142:145], v[166:169], v[30:33]
	v_mfma_f32_16x16x32_bf16 v[22:25], v[134:137], v[174:177], v[22:25]
	v_mfma_f32_16x16x32_bf16 v[18:21], v[142:145], v[174:177], v[18:21]
	v_mfma_f32_16x16x32_bf16 v[58:61], v[134:137], v[182:185], v[58:61]
	v_mfma_f32_16x16x32_bf16 v[50:53], v[142:145], v[182:185], v[50:53]
	v_mfma_f32_16x16x32_bf16 v[62:65], v[134:137], v[190:193], v[62:65]
	v_mfma_f32_16x16x32_bf16 v[54:57], v[142:145], v[190:193], v[54:57]
	s_setprio 0
	s_setprio 1
	v_mfma_f32_16x16x32_bf16 v[14:17], v[146:149], v[162:165], v[14:17]
	v_mfma_f32_16x16x32_bf16 v[10:13], v[154:157], v[162:165], v[10:13]
	v_mfma_f32_16x16x32_bf16 v[6:9], v[146:149], v[170:173], v[6:9]
	v_mfma_f32_16x16x32_bf16 v[2:5], v[154:157], v[170:173], v[2:5]
	v_mfma_f32_16x16x32_bf16 v[42:45], v[146:149], v[178:181], v[42:45]
	v_mfma_f32_16x16x32_bf16 v[26:29], v[154:157], v[178:181], v[26:29]
	v_mfma_f32_16x16x32_bf16 v[46:49], v[146:149], v[186:189], v[46:49]
	v_mfma_f32_16x16x32_bf16 v[38:41], v[154:157], v[186:189], v[38:41]
	v_mfma_f32_16x16x32_bf16 v[14:17], v[150:153], v[166:169], v[14:17]
	v_mfma_f32_16x16x32_bf16 v[10:13], v[158:161], v[166:169], v[10:13]
	v_mfma_f32_16x16x32_bf16 v[6:9], v[150:153], v[174:177], v[6:9]
	v_mfma_f32_16x16x32_bf16 v[2:5], v[158:161], v[174:177], v[2:5]
	v_mfma_f32_16x16x32_bf16 v[42:45], v[150:153], v[182:185], v[42:45]
	v_mfma_f32_16x16x32_bf16 v[26:29], v[158:161], v[182:185], v[26:29]
	v_mfma_f32_16x16x32_bf16 v[46:49], v[150:153], v[190:193], v[46:49]
	v_mfma_f32_16x16x32_bf16 v[38:41], v[158:161], v[190:193], v[38:41]
	s_setprio 0
	s_barrier
	s_add_i32 vcc_hi, vcc_hi, 2
	s_add_u32 s4, s4, 0x100
	s_addc_u32 s5, s5, 0
	s_add_u32 s46, s46, 0x100
	s_addc_u32 s47, s47, 0
	s_cmp_gt_u32 vcc_hi, 13
	s_cbranch_scc0 .LBB0_556
	s_mov_b32 s98, 0xbfb8aa3b
	s_and_b64 vcc, exec, s[34:35]
	s_cbranch_vccz .LBB0_559
	s_barrier

; __device__ __forceinline__ unsigned cvt_pk_bf16(float lo, float hi) { unsigned r; asm volatile("v_cvt_pk_bf16_f32 %0, %1, %2" : "=v"(r) : "v"(lo), "v"(hi)); return r; }
;     __device__ __forceinline__ void run(f32x4 (&acc)[2][2][4][2], const Unit& u, int wr, int wc, int fr_, int fq_, int par) const {
;     ...
;             char* gb = (char*)(G + (long)growu * 2816 + cu);
; #pragma unroll
;             for (int m = 0; m < 4; ++m) {
;                 const int grow = grow0 + m, rl = ai * HALF + wr * 64 + 4 * fr + m;
;                 if (rl >= 2 && grow < nrows) {
;                     u32x4 w; float o[8];
; #pragma unroll
;                     for (int n = 0; n < 2; ++n)
; #pragma unroll
;                         for (int j = 0; j < 4; ++j) { const float g = acc[ai][0][m][n][j], x = acc[ai][1][m][n][j]; o[n * 4 + j] = g * __builtin_amdgcn_rcpf(1.0f + __expf(-g)) * x; }
;                     w.x = cvt_pk_bf16(o[0], o[1]); w.y = cvt_pk_bf16(o[2], o[3]); w.z = cvt_pk_bf16(o[4], o[5]); w.w = cvt_pk_bf16(o[6], o[7]);
;                     *(u32x4*)(gb + (unsigned)(((4 * fr + m) * 2816 + 8 * fq) * 2)) = w;
;                 }
.LBB0_597:
	s_lshl_b32 s4, s92, 7
	s_or_b32 s4, s4, s7
	s_ashr_i32 s5, s4, 31
	s_mul_hi_i32 s22, s15, 0x1600
	s_mulk_i32 s15, 0x1600
	s_add_u32 s15, s12, s15
	v_or_b32_e32 v166, s6, v251
	s_addc_u32 s22, s13, s22
	s_lshl_b64 s[46:47], s[4:5], 1
	v_lshlrev_b32_e32 v68, 3, v250
	s_add_u32 s58, s15, s46
	v_cmp_lt_i32_e32 vcc, 1, v166
	v_cmp_gt_i32_e64 s[4:5], s42, v252
	v_mul_u32_u24_e32 v69, 0x2c00, v253
	s_addc_u32 s59, s22, s47
	s_and_b64 s[94:95], vcc, s[4:5]
	v_add_lshl_u32 v167, v69, v68, 1
	s_and_saveexec_b64 s[4:5], s[94:95]
	s_cbranch_execz .LBB0_599
	v_mul_f32_e32 v70, s98, v159
	v_mul_f32_e32 v71, s98, v160
	v_mul_f32_e32 v72, s98, v161
	v_mul_f32_e32 v73, s98, v146
	v_mul_f32_e32 v69, s98, v158
	v_exp_f32_e32 v70, v70
	v_exp_f32_e32 v71, v71
	v_exp_f32_e32 v72, v72
	v_exp_f32_e32 v73, v73
	v_mul_f32_e32 v74, s98, v147
	v_mul_f32_e32 v75, s98, v148
	v_mul_f32_e32 v76, s98, v149
	v_exp_f32_e32 v69, v69
	v_exp_f32_e32 v74, v74
	v_exp_f32_e32 v75, v75
	v_exp_f32_e32 v76, v76
	v_add_f32_e32 v70, 1.0, v70
	v_add_f32_e32 v71, 1.0, v71
	v_add_f32_e32 v72, 1.0, v72
	v_add_f32_e32 v73, 1.0, v73
	v_add_f32_e32 v69, 1.0, v69
	v_rcp_f32_e32 v70, v70
	v_rcp_f32_e32 v71, v71
	v_rcp_f32_e32 v72, v72
	v_rcp_f32_e32 v73, v73
	v_add_f32_e32 v74, 1.0, v74
	v_add_f32_e32 v75, 1.0, v75
	v_add_f32_e32 v76, 1.0, v76
	v_rcp_f32_e32 v69, v69
	v_rcp_f32_e32 v74, v74
	v_rcp_f32_e32 v75, v75
	v_rcp_f32_e32 v76, v76
	v_mul_f32_e32 v70, v159, v70
	v_mul_f32_e32 v71, v160, v71
	v_mul_f32_e32 v72, v161, v72
	v_mul_f32_e32 v73, v146, v73
	v_mul_f32_e32 v69, v158, v69
	v_mul_f32_e32 v70, v139, v70
	v_mul_f32_e32 v71, v140, v71
	v_mul_f32_e32 v72, v141, v72
	v_mul_f32_e32 v73, v162, v73
	v_mul_f32_e32 v74, v147, v74
	v_mul_f32_e32 v75, v148, v75
	v_mul_f32_e32 v76, v149, v76
	v_mul_f32_e32 v69, v138, v69
	v_mul_f32_e32 v74, v163, v74
	v_mul_f32_e32 v75, v164, v75
	v_mul_f32_e32 v76, v165, v76
	v_cvt_pk_bf16_f32 v70, v69, v70
	v_cvt_pk_bf16_f32 v71, v71, v72
	v_cvt_pk_bf16_f32 v72, v73, v74
	v_cvt_pk_bf16_f32 v73, v75, v76
	global_store_dwordx4 v167, v[70:73], s[58:59]
.LBB0_599:
	s_or_b64 exec, exec, s[4:5]
	v_or_b32_e32 v69, 1, v252
	v_cmp_lt_i32_e32 vcc, 0, v166
	v_cmp_gt_i32_e64 s[4:5], s42, v69
	s_and_b64 s[94:95], vcc, s[4:5]
	s_movk_i32 s4, 0x2c00
	v_mad_u32_u24 v68, v253, s4, v68
	v_mov_b32_e32 v69, 0x1600
	v_lshl_add_u32 v138, v68, 1, v69
	s_and_saveexec_b64 s[4:5], s[94:95]
	s_cbranch_execz .LBB0_601
	v_mul_f32_e32 v70, s98, v151
	v_mul_f32_e32 v71, s98, v152
	v_mul_f32_e32 v72, s98, v153
	v_mul_f32_e32 v73, s98, v130
	v_mul_f32_e32 v69, s98, v150
	v_exp_f32_e32 v70, v70
	v_exp_f32_e32 v71, v71
	v_exp_f32_e32 v72, v72
	v_exp_f32_e32 v73, v73
	v_mul_f32_e32 v74, s98, v131
	v_mul_f32_e32 v75, s98, v132
	v_mul_f32_e32 v76, s98, v133
	v_exp_f32_e32 v69, v69
	v_exp_f32_e32 v74, v74
	v_exp_f32_e32 v75, v75
	v_exp_f32_e32 v76, v76
	v_add_f32_e32 v70, 1.0, v70
	v_add_f32_e32 v71, 1.0, v71
	v_add_f32_e32 v72, 1.0, v72
	v_add_f32_e32 v73, 1.0, v73
	v_add_f32_e32 v69, 1.0, v69
	v_rcp_f32_e32 v70, v70
	v_rcp_f32_e32 v71, v71
	v_rcp_f32_e32 v72, v72
	v_rcp_f32_e32 v73, v73
	v_add_f32_e32 v74, 1.0, v74
	v_add_f32_e32 v75, 1.0, v75
	v_add_f32_e32 v76, 1.0, v76
	v_rcp_f32_e32 v69, v69
	v_rcp_f32_e32 v74, v74
	v_rcp_f32_e32 v75, v75
	v_rcp_f32_e32 v76, v76
	v_mul_f32_e32 v70, v151, v70
	v_mul_f32_e32 v71, v152, v71
	v_mul_f32_e32 v72, v153, v72
	v_mul_f32_e32 v73, v130, v73
	v_mul_f32_e32 v69, v150, v69
	v_mul_f32_e32 v70, v123, v70
	v_mul_f32_e32 v71, v124, v71
	v_mul_f32_e32 v72, v125, v72
	v_mul_f32_e32 v73, v154, v73
	v_mul_f32_e32 v74, v131, v74
	v_mul_f32_e32 v75, v132, v75
	v_mul_f32_e32 v76, v133, v76
	v_mul_f32_e32 v69, v122, v69
	v_mul_f32_e32 v74, v155, v74
	v_mul_f32_e32 v75, v156, v75
	v_mul_f32_e32 v76, v157, v76
	v_cvt_pk_bf16_f32 v70, v69, v70
	v_cvt_pk_bf16_f32 v71, v71, v72
	v_cvt_pk_bf16_f32 v72, v73, v74
	v_cvt_pk_bf16_f32 v73, v75, v76
	global_store_dwordx4 v138, v[70:73], s[58:59]
; __device__ __forceinline__ unsigned cvt_pk_bf16(float lo, float hi) { unsigned r; asm volatile("v_cvt_pk_bf16_f32 %0, %1, %2" : "=v"(r) : "v"(lo), "v"(hi)); return r; }
;     __device__ __forceinline__ void run(f32x4 (&acc)[2][2][4][2], const Unit& u, int wr, int wc, int fr_, int fq_, int par) const {
;     ...
;             for (int m = 0; m < 4; ++m) {
;                 const int grow = grow0 + m, rl = ai * HALF + wr * 64 + 4 * fr + m;
;                 if (rl >= 2 && grow < nrows) {
;                     u32x4 w; float o[8];
; #pragma unroll
;                     for (int n = 0; n < 2; ++n)
; #pragma unroll
;                         for (int j = 0; j < 4; ++j) { const float g = acc[ai][0][m][n][j], x = acc[ai][1][m][n][j]; o[n * 4 + j] = g * __builtin_amdgcn_rcpf(1.0f + __expf(-g)) * x; }
;                     w.x = cvt_pk_bf16(o[0], o[1]); w.y = cvt_pk_bf16(o[2], o[3]); w.z = cvt_pk_bf16(o[4], o[5]); w.w = cvt_pk_bf16(o[6], o[7]);
;                     *(u32x4*)(gb + (unsigned)(((4 * fr + m) * 2816 + 8 * fq) * 2)) = w;
;                 }
.LBB0_601:
	s_or_b64 exec, exec, s[4:5]
	s_mov_b32 s4, 0x80fe
	v_cmp_gt_i32_e32 vcc, s4, v252
	v_mov_b32_e32 v69, 0x2c00
	s_and_b64 s[94:95], s[60:61], vcc
	v_lshl_add_u32 v131, v68, 1, v69
	s_and_saveexec_b64 s[4:5], s[94:95]
	s_cbranch_execz .LBB0_603
	v_mul_f32_e32 v70, s98, v135
	v_mul_f32_e32 v71, s98, v136
	v_mul_f32_e32 v72, s98, v137
	v_mul_f32_e32 v73, s98, v114
	v_mul_f32_e32 v69, s98, v134
	v_exp_f32_e32 v70, v70
	v_exp_f32_e32 v71, v71
	v_exp_f32_e32 v72, v72
	v_exp_f32_e32 v73, v73
	v_mul_f32_e32 v74, s98, v115
	v_mul_f32_e32 v75, s98, v116
	v_mul_f32_e32 v76, s98, v117
	v_exp_f32_e32 v69, v69
	v_exp_f32_e32 v74, v74
	v_exp_f32_e32 v75, v75
	v_exp_f32_e32 v76, v76
	v_add_f32_e32 v70, 1.0, v70
	v_add_f32_e32 v71, 1.0, v71
	v_add_f32_e32 v72, 1.0, v72
	v_add_f32_e32 v73, 1.0, v73
	v_add_f32_e32 v69, 1.0, v69
	v_rcp_f32_e32 v70, v70
	v_rcp_f32_e32 v71, v71
	v_rcp_f32_e32 v72, v72
	v_rcp_f32_e32 v73, v73
	v_add_f32_e32 v74, 1.0, v74
	v_add_f32_e32 v75, 1.0, v75
	v_add_f32_e32 v76, 1.0, v76
	v_rcp_f32_e32 v69, v69
	v_rcp_f32_e32 v74, v74
	v_rcp_f32_e32 v75, v75
	v_rcp_f32_e32 v76, v76
	v_mul_f32_e32 v70, v135, v70
	v_mul_f32_e32 v71, v136, v71
	v_mul_f32_e32 v72, v137, v72
	v_mul_f32_e32 v73, v114, v73
	v_mul_f32_e32 v69, v134, v69
	v_mul_f32_e32 v70, v111, v70
	v_mul_f32_e32 v71, v112, v71
	v_mul_f32_e32 v72, v113, v72
	v_mul_f32_e32 v73, v142, v73
	v_mul_f32_e32 v74, v115, v74
	v_mul_f32_e32 v75, v116, v75
	v_mul_f32_e32 v76, v117, v76
	v_mul_f32_e32 v69, v110, v69
	v_mul_f32_e32 v74, v143, v74
	v_mul_f32_e32 v75, v144, v75
	v_mul_f32_e32 v76, v145, v76
	v_cvt_pk_bf16_f32 v70, v69, v70
	v_cvt_pk_bf16_f32 v71, v71, v72
	v_cvt_pk_bf16_f32 v72, v73, v74
	v_cvt_pk_bf16_f32 v73, v75, v76
	global_store_dwordx4 v131, v[70:73], s[58:59]
.LBB0_603:
	s_or_b64 exec, exec, s[4:5]
	s_mov_b32 s4, 0x80fd
	v_cmp_gt_i32_e32 vcc, s4, v252
	v_mov_b32_e32 v69, 0x4200
	s_and_b64 s[94:95], s[60:61], vcc
	v_lshl_add_u32 v130, v68, 1, v69
	s_and_saveexec_b64 s[4:5], s[94:95]
	s_cbranch_execz .LBB0_605
	v_mul_f32_e32 v68, s98, v118
	v_mul_f32_e32 v69, s98, v119
	v_mul_f32_e32 v70, s98, v120
	v_mul_f32_e32 v71, s98, v121
	v_exp_f32_e32 v68, v68
	v_exp_f32_e32 v69, v69
	v_exp_f32_e32 v70, v70
	v_exp_f32_e32 v71, v71
	v_mul_f32_e32 v72, s98, v98
	v_mul_f32_e32 v73, s98, v99
	v_mul_f32_e32 v74, s98, v100
	v_mul_f32_e32 v75, s98, v101
	v_exp_f32_e32 v72, v72
	v_exp_f32_e32 v73, v73
	v_exp_f32_e32 v74, v74
	v_exp_f32_e32 v75, v75
	v_add_f32_e32 v68, 1.0, v68
	v_add_f32_e32 v69, 1.0, v69
	v_add_f32_e32 v70, 1.0, v70
	v_add_f32_e32 v71, 1.0, v71
	v_rcp_f32_e32 v68, v68
	v_rcp_f32_e32 v69, v69
	v_rcp_f32_e32 v70, v70
	v_rcp_f32_e32 v71, v71
	v_add_f32_e32 v72, 1.0, v72
	v_add_f32_e32 v73, 1.0, v73
	v_add_f32_e32 v74, 1.0, v74
	v_add_f32_e32 v75, 1.0, v75
	v_rcp_f32_e32 v72, v72
	v_rcp_f32_e32 v73, v73
	v_rcp_f32_e32 v74, v74
	v_rcp_f32_e32 v75, v75
	v_mul_f32_e32 v68, v118, v68
	v_mul_f32_e32 v69, v119, v69
	v_mul_f32_e32 v70, v120, v70
	v_mul_f32_e32 v71, v121, v71
	v_mul_f32_e32 v68, v94, v68
	v_mul_f32_e32 v69, v95, v69
	v_mul_f32_e32 v70, v96, v70
	v_mul_f32_e32 v71, v97, v71
	v_mul_f32_e32 v72, v98, v72
	v_mul_f32_e32 v73, v99, v73
	v_mul_f32_e32 v74, v100, v74
	v_mul_f32_e32 v75, v101, v75
	v_mul_f32_e32 v72, v126, v72
	v_mul_f32_e32 v73, v127, v73
	v_mul_f32_e32 v74, v128, v74
	v_mul_f32_e32 v75, v129, v75
	v_cvt_pk_bf16_f32 v68, v68, v69
	v_cvt_pk_bf16_f32 v69, v70, v71
	v_cvt_pk_bf16_f32 v70, v72, v73
	v_cvt_pk_bf16_f32 v71, v74, v75
	global_store_dwordx4 v130, v[68:71], s[58:59]

; __device__ __forceinline__ unsigned cvt_pk_bf16(float lo, float hi) { unsigned r; asm volatile("v_cvt_pk_bf16_f32 %0, %1, %2" : "=v"(r) : "v"(lo), "v"(hi)); return r; }
;     __device__ __forceinline__ void run(f32x4 (&acc)[2][2][4][2], const Unit& u, int wr, int wc, int fr_, int fq_, int par) const {
;     ...
;             char* gb = (char*)(G + (long)growu * 2816 + cu);
; #pragma unroll
;             for (int m = 0; m < 4; ++m) {
;                 const int grow = grow0 + m, rl = ai * HALF + wr * 64 + 4 * fr + m;
;                 if (rl >= 2 && grow < nrows) {
;                     u32x4 w; float o[8];
; #pragma unroll
;                     for (int n = 0; n < 2; ++n)
; #pragma unroll
;                         for (int j = 0; j < 4; ++j) { const float g = acc[ai][0][m][n][j], x = acc[ai][1][m][n][j]; o[n * 4 + j] = g * __builtin_amdgcn_rcpf(1.0f + __expf(-g)) * x; }
;                     w.x = cvt_pk_bf16(o[0], o[1]); w.y = cvt_pk_bf16(o[2], o[3]); w.z = cvt_pk_bf16(o[4], o[5]); w.w = cvt_pk_bf16(o[6], o[7]);
;                     *(u32x4*)(gb + (unsigned)(((4 * fr + m) * 2816 + 8 * fq) * 2)) = w;
;                 }
.LBB0_608:
	s_mul_hi_i32 s4, s14, 0x1600
	s_mulk_i32 s14, 0x1600
	s_add_u32 s5, s12, s14
	s_addc_u32 s4, s13, s4
	s_add_u32 s46, s5, s46
	s_addc_u32 s47, s4, s47
	s_movk_i32 s4, 0xff81
	v_cmp_lt_i32_e32 vcc, s4, v166
	v_cmp_gt_i32_e64 s[4:5], s42, v132
	s_and_b64 s[14:15], vcc, s[4:5]
	s_and_saveexec_b64 s[4:5], s[14:15]
	s_cbranch_execz .LBB0_610
	v_mul_f32_e32 v26, s98, v66
	v_mul_f32_e32 v27, s98, v67
	v_mul_f32_e32 v28, s98, v68
	v_mul_f32_e32 v29, s98, v69
	v_exp_f32_e32 v26, v26
	v_exp_f32_e32 v27, v27
	v_exp_f32_e32 v28, v28
	v_exp_f32_e32 v29, v29
	v_mul_f32_e32 v38, s98, v74
	v_mul_f32_e32 v39, s98, v75
	v_mul_f32_e32 v40, s98, v76
	v_mul_f32_e32 v41, s98, v77
	v_exp_f32_e32 v38, v38
	v_exp_f32_e32 v39, v39
	v_exp_f32_e32 v40, v40
	v_exp_f32_e32 v41, v41
	v_add_f32_e32 v26, 1.0, v26
	v_add_f32_e32 v27, 1.0, v27
	v_add_f32_e32 v28, 1.0, v28
	v_add_f32_e32 v29, 1.0, v29
	v_rcp_f32_e32 v26, v26
	v_rcp_f32_e32 v27, v27
	v_rcp_f32_e32 v28, v28
	v_rcp_f32_e32 v29, v29
	v_add_f32_e32 v38, 1.0, v38
	v_add_f32_e32 v39, 1.0, v39
	v_add_f32_e32 v40, 1.0, v40
	v_add_f32_e32 v41, 1.0, v41
	v_rcp_f32_e32 v38, v38
	v_rcp_f32_e32 v39, v39
	v_rcp_f32_e32 v40, v40
	v_rcp_f32_e32 v41, v41
	v_mul_f32_e32 v26, v66, v26
	v_mul_f32_e32 v27, v67, v27
	v_mul_f32_e32 v28, v68, v28
	v_mul_f32_e32 v29, v69, v29
	v_mul_f32_e32 v26, v90, v26
	v_mul_f32_e32 v27, v91, v27
	v_mul_f32_e32 v28, v92, v28
	v_mul_f32_e32 v29, v93, v29
	v_mul_f32_e32 v38, v74, v38
	v_mul_f32_e32 v39, v75, v39
	v_mul_f32_e32 v40, v76, v40
	v_mul_f32_e32 v41, v77, v41
	v_mul_f32_e32 v38, v94, v38
	v_mul_f32_e32 v39, v95, v39
	v_mul_f32_e32 v40, v96, v40
	v_mul_f32_e32 v41, v97, v41
	v_cvt_pk_bf16_f32 v26, v26, v27
	v_cvt_pk_bf16_f32 v27, v28, v29
	v_cvt_pk_bf16_f32 v28, v38, v39
	v_cvt_pk_bf16_f32 v29, v40, v41
	global_store_dwordx4 v167, v[26:29], s[46:47]
.LBB0_610:
	s_or_b64 exec, exec, s[4:5]
	s_movk_i32 s4, 0xff80
	v_or_b32_e32 v26, 1, v132
	v_cmp_lt_i32_e32 vcc, s4, v166
	v_cmp_gt_i32_e64 s[4:5], s42, v26
	s_and_b64 s[14:15], vcc, s[4:5]
	s_and_saveexec_b64 s[4:5], s[14:15]
	s_cbranch_execz .LBB0_612
	v_mul_f32_e32 v26, s98, v18
	v_exp_f32_e32 v26, v26
	v_mul_f32_e32 v27, s98, v31
	v_mul_f32_e32 v28, s98, v32
	v_mul_f32_e32 v29, s98, v33
	v_add_f32_e32 v26, 1.0, v26
	v_rcp_f32_e32 v26, v26
	v_exp_f32_e32 v27, v27
	v_exp_f32_e32 v28, v28
	v_exp_f32_e32 v29, v29
	v_mul_f32_e32 v18, v18, v26
	v_mul_f32_e32 v26, s98, v19
	v_exp_f32_e32 v26, v26
	v_add_f32_e32 v27, 1.0, v27
	v_add_f32_e32 v28, 1.0, v28
	v_add_f32_e32 v29, 1.0, v29
	v_add_f32_e32 v26, 1.0, v26
	v_rcp_f32_e32 v26, v26
	v_rcp_f32_e32 v27, v27
	v_rcp_f32_e32 v28, v28
	v_rcp_f32_e32 v29, v29
	v_mul_f32_e32 v19, v19, v26
	v_mul_f32_e32 v26, s98, v20
	v_exp_f32_e32 v26, v26
	v_mul_f32_e32 v18, v82, v18
	v_mul_f32_e32 v19, v83, v19
	v_mul_f32_e32 v27, v31, v27
	v_add_f32_e32 v26, 1.0, v26
	v_rcp_f32_e32 v26, v26
	v_mul_f32_e32 v28, v32, v28
	v_mul_f32_e32 v29, v33, v29
	v_mul_f32_e32 v27, v87, v27
	v_mul_f32_e32 v20, v20, v26
	v_mul_f32_e32 v26, s98, v21
	v_exp_f32_e32 v26, v26
	v_mul_f32_e32 v20, v84, v20
	v_mul_f32_e32 v28, v88, v28
	v_mul_f32_e32 v29, v89, v29
	v_add_f32_e32 v26, 1.0, v26
	v_rcp_f32_e32 v26, v26
	v_cvt_pk_bf16_f32 v18, v18, v19
	s_nop 0
	v_mul_f32_e32 v21, v21, v26
	v_mul_f32_e32 v26, s98, v30
	v_exp_f32_e32 v26, v26
	v_mul_f32_e32 v21, v85, v21
	v_cvt_pk_bf16_f32 v19, v20, v21
	v_add_f32_e32 v26, 1.0, v26
	v_rcp_f32_e32 v26, v26
	s_nop 0
	v_mul_f32_e32 v26, v30, v26
	v_mul_f32_e32 v26, v86, v26
	v_cvt_pk_bf16_f32 v20, v26, v27
	v_cvt_pk_bf16_f32 v21, v28, v29
	global_store_dwordx4 v138, v[18:21], s[46:47]
; __device__ __forceinline__ unsigned cvt_pk_bf16(float lo, float hi) { unsigned r; asm volatile("v_cvt_pk_bf16_f32 %0, %1, %2" : "=v"(r) : "v"(lo), "v"(hi)); return r; }
;     __device__ __forceinline__ void run(f32x4 (&acc)[2][2][4][2], const Unit& u, int wr, int wc, int fr_, int fq_, int par) const {
;     ...
;             for (int m = 0; m < 4; ++m) {
;                 const int grow = grow0 + m, rl = ai * HALF + wr * 64 + 4 * fr + m;
;                 if (rl >= 2 && grow < nrows) {
;                     u32x4 w; float o[8];
; #pragma unroll
;                     for (int n = 0; n < 2; ++n)
; #pragma unroll
;                         for (int j = 0; j < 4; ++j) { const float g = acc[ai][0][m][n][j], x = acc[ai][1][m][n][j]; o[n * 4 + j] = g * __builtin_amdgcn_rcpf(1.0f + __expf(-g)) * x; }
;                     w.x = cvt_pk_bf16(o[0], o[1]); w.y = cvt_pk_bf16(o[2], o[3]); w.z = cvt_pk_bf16(o[4], o[5]); w.w = cvt_pk_bf16(o[6], o[7]);
;                     *(u32x4*)(gb + (unsigned)(((4 * fr + m) * 2816 + 8 * fq) * 2)) = w;
;                 }
.LBB0_612:
	s_or_b64 exec, exec, s[4:5]
	s_movk_i32 s4, 0xff7f
	v_cmp_lt_i32_e32 vcc, s4, v166
	s_mov_b32 s4, 0x80fe
	v_cmp_gt_i32_e64 s[4:5], s4, v132
	s_and_b64 s[14:15], vcc, s[4:5]
	s_and_saveexec_b64 s[4:5], s[14:15]
	s_cbranch_execz .LBB0_614
	v_mul_f32_e32 v18, s98, v10
	v_exp_f32_e32 v18, v18
	s_nop 0
	v_add_f32_e32 v18, 1.0, v18
	v_rcp_f32_e32 v18, v18
	s_nop 0
	v_mul_f32_e32 v10, v10, v18
	v_mul_f32_e32 v18, s98, v11
	v_exp_f32_e32 v18, v18
	v_mul_f32_e32 v10, v70, v10
	v_add_f32_e32 v18, 1.0, v18
	v_rcp_f32_e32 v18, v18
	s_nop 0
	v_mul_f32_e32 v11, v11, v18
	v_mul_f32_e32 v18, s98, v12
	v_exp_f32_e32 v18, v18
	v_mul_f32_e32 v11, v71, v11
	v_cvt_pk_bf16_f32 v10, v10, v11
	v_add_f32_e32 v18, 1.0, v18
	v_rcp_f32_e32 v18, v18
	s_nop 0
	v_mul_f32_e32 v12, v12, v18
	v_mul_f32_e32 v18, s98, v13
	v_exp_f32_e32 v18, v18
	v_mul_f32_e32 v12, v72, v12
	v_add_f32_e32 v18, 1.0, v18
	v_rcp_f32_e32 v18, v18
	s_nop 0
	v_mul_f32_e32 v13, v13, v18
	v_mul_f32_e32 v18, s98, v14
	v_exp_f32_e32 v18, v18
	v_mul_f32_e32 v13, v73, v13
	v_cvt_pk_bf16_f32 v11, v12, v13
	v_add_f32_e32 v18, 1.0, v18
	v_rcp_f32_e32 v18, v18
	s_nop 0
	v_mul_f32_e32 v14, v14, v18
	v_mul_f32_e32 v18, s98, v15
	v_exp_f32_e32 v18, v18
	v_mul_f32_e32 v14, v78, v14
	v_add_f32_e32 v18, 1.0, v18
	v_rcp_f32_e32 v18, v18
	s_nop 0
	v_mul_f32_e32 v15, v15, v18
	v_mul_f32_e32 v18, s98, v16
	v_exp_f32_e32 v18, v18
	v_mul_f32_e32 v15, v79, v15
	v_cvt_pk_bf16_f32 v12, v14, v15
	v_add_f32_e32 v18, 1.0, v18
	v_rcp_f32_e32 v18, v18
	s_nop 0
	v_mul_f32_e32 v16, v16, v18
	v_mul_f32_e32 v18, s98, v17
	v_exp_f32_e32 v18, v18
	v_mul_f32_e32 v16, v80, v16
	v_add_f32_e32 v18, 1.0, v18
	v_rcp_f32_e32 v18, v18
	s_nop 0
	v_mul_f32_e32 v17, v17, v18
	v_mul_f32_e32 v17, v81, v17
	v_cvt_pk_bf16_f32 v13, v16, v17
	global_store_dwordx4 v131, v[10:13], s[46:47]
.LBB0_614:
	s_or_b64 exec, exec, s[4:5]
	s_movk_i32 s4, 0xff7e
	v_cmp_lt_i32_e32 vcc, s4, v166
	s_mov_b32 s4, 0x80fd
	v_cmp_gt_i32_e64 s[4:5], s4, v132
	s_and_b64 s[14:15], vcc, s[4:5]
	s_and_saveexec_b64 s[4:5], s[14:15]
	s_cbranch_execz .LBB0_616
	v_mul_f32_e32 v10, s98, v2
	v_exp_f32_e32 v10, v10
	s_nop 0
	v_add_f32_e32 v10, 1.0, v10
	v_rcp_f32_e32 v10, v10
	s_nop 0
	v_mul_f32_e32 v2, v2, v10
	v_mul_f32_e32 v10, s98, v3
	v_exp_f32_e32 v10, v10
	v_mul_f32_e32 v2, v22, v2
	v_add_f32_e32 v10, 1.0, v10
	v_rcp_f32_e32 v10, v10
	s_nop 0
	v_mul_f32_e32 v3, v3, v10
	v_mul_f32_e32 v10, s98, v4
	v_exp_f32_e32 v10, v10
	v_mul_f32_e32 v3, v23, v3
	v_cvt_pk_bf16_f32 v2, v2, v3
	v_add_f32_e32 v10, 1.0, v10
	v_rcp_f32_e32 v10, v10
	s_nop 0
	v_mul_f32_e32 v4, v4, v10
	v_mul_f32_e32 v10, s98, v5
	v_exp_f32_e32 v10, v10
	v_mul_f32_e32 v4, v24, v4
	v_add_f32_e32 v10, 1.0, v10
	v_rcp_f32_e32 v10, v10
	s_nop 0
	v_mul_f32_e32 v5, v5, v10
	v_mul_f32_e32 v10, s98, v6
	v_exp_f32_e32 v10, v10
	v_mul_f32_e32 v5, v25, v5
	v_cvt_pk_bf16_f32 v3, v4, v5
	v_add_f32_e32 v10, 1.0, v10
	v_rcp_f32_e32 v10, v10
	s_nop 0
	v_mul_f32_e32 v6, v6, v10
	v_mul_f32_e32 v10, s98, v7
	v_exp_f32_e32 v10, v10
	v_mul_f32_e32 v6, v34, v6
	v_add_f32_e32 v10, 1.0, v10
	v_rcp_f32_e32 v10, v10
	s_nop 0
	v_mul_f32_e32 v7, v7, v10
	v_mul_f32_e32 v10, s98, v8
	v_exp_f32_e32 v10, v10
	v_mul_f32_e32 v7, v35, v7
	v_cvt_pk_bf16_f32 v4, v6, v7
	v_add_f32_e32 v10, 1.0, v10
	v_rcp_f32_e32 v10, v10
	s_nop 0
	v_mul_f32_e32 v8, v8, v10
	v_mul_f32_e32 v10, s98, v9
	v_exp_f32_e32 v10, v10
	v_mul_f32_e32 v8, v36, v8
	v_add_f32_e32 v10, 1.0, v10
	v_rcp_f32_e32 v10, v10
	s_nop 0
	v_mul_f32_e32 v9, v9, v10
	v_mul_f32_e32 v9, v37, v9
	v_cvt_pk_bf16_f32 v5, v8, v9
	global_store_dwordx4 v130, v[2:5], s[46:47]
